# conv2d: wave-task assignment transposed so every workgroup has 6 waves with 3 tasks and 2 with 2 (even per-CU load)
# baseline (speedup 1.0000x reference)
.LBB0_928:
	s_cmp_lt_i32 s76, 12
	s_cselect_b64 s[16:17], -1, 0
	s_and_b64 s[4:5], s[16:17], s[46:47]
	s_andn2_b64 vcc, exec, s[4:5]
	s_cbranch_vccnz .LBB0_979
	s_and_b32 s4, s2, 7
	s_mulk_i32 s4, 0x2c0
	s_lshr_b32 s5, s2, 3
	s_and_b32 s3, s38, 7
	s_lshl_b32 s10, s2, 3
	s_add_i32 s11, s4, s5
	s_add_i32 s12, s4, 0x2c0
	s_cmp_eq_u32 s3, 0
	s_cselect_b64 s[6:7], -1, 0
	s_and_b64 s[4:5], s[6:7], exec
	s_cselect_b32 s3, s11, s10
	s_waitcnt vmcnt(0)
	v_lshlrev_b32_e32 v166, 5, v197
	v_cndmask_b32_e64 v166, v197, v166, s[6:7]
	v_add_u32_e32 v166, s3, v166
	s_cselect_b32 s27, s12, 0x1600
	s_mov_b64 s[8:9], s[0:1]
	s_movk_i32 s3, 0x1600
	v_cmp_gt_i32_e32 vcc, s27, v166
	s_and_saveexec_b64 s[18:19], vcc
	s_cbranch_execz .LBB0_978
	s_load_dwordx4 s[12:15], s[8:9], 0xb8
	s_load_dwordx2 s[20:21], s[8:9], 0xe0
	s_and_b32 s10, s38, -8
	s_lshl_b32 s11, s38, 3
	s_and_b64 s[4:5], s[6:7], exec
	s_cselect_b32 s29, s10, s11
	s_waitcnt lgkmcnt(0)
	s_add_u32 s22, s20, 0xd200e00
	v_lshlrev_b32_e32 v0, 2, v196
	s_addc_u32 s23, s21, 0
	v_and_b32_e32 v167, 0xfc, v0
	s_mov_b64 s[24:25], 0
	s_mov_b32 s39, 0x2e8ba2e9
	s_movk_i32 s48, 0x2000
	s_movk_i32 s49, 0x5000
	s_mov_b32 s50, 0x8000
	s_mov_b32 s51, 0xb000
	s_mov_b32 s52, 0xd000
	s_mov_b32 s53, 0x10000
	s_mov_b32 s54, 0x13000
	s_mov_b32 s55, 0x16000
	s_movk_i32 s56, 0x7c
	s_mov_b32 s57, 0x2c00000
	v_mov_b64_e32 v[40:41], s[22:23]
	s_movk_i32 s58, 0x80
	v_mov_b32_e32 v42, 0
	s_movk_i32 s59, 0x100
	s_mov_b32 s60, 0x160000
	s_mov_b32 s61, 0x23200000
	s_mov_b32 s26, 0x3dd2d3e7
	s_mov_b32 s28, 0xc0135761
	s_mov_b32 s62, 0x23202000
	s_mov_b32 s63, 0x23203000
	s_mov_b32 s98, s61
	s_mov_b32 s99, 0
	s_mov_b32 s100, s63
	s_mov_b32 s101, 0
	s_branch .LBB0_932

.LBB0_949:
	s_or_b64 exec, exec, s[10:11]
	v_add_co_u32_e32 v86, vcc, s63, v128
	v_pk_mul_f32 v[94:95], v[6:7], v[76:77]
	s_nop 0
	v_addc_co_u32_e32 v87, vcc, 0, v129, vcc
	flat_load_dwordx2 v[88:89], v[86:87] offset:2560
	v_lshl_add_u64 v[178:179], v[116:117], 0, s[100:101]
	v_lshl_add_u64 v[180:181], v[110:111], 0, s[100:101]
	v_lshl_add_u64 v[182:183], v[100:101], 0, s[100:101]
	global_load_dwordx2 v[184:185], v[178:179], off offset:2560
	global_load_dwordx2 v[186:187], v[180:181], off offset:2560
	global_load_dwordx2 v[188:189], v[182:183], off offset:2560
	v_pk_mul_f32 v[96:97], v[4:5], v[72:73]
	v_lshlrev_b32_e32 v62, 16, v148
	v_and_b32_e32 v63, 0xffff0000, v148
	v_lshlrev_b32_e32 v64, 16, v149
	v_and_b32_e32 v65, 0xffff0000, v149
	v_pk_mul_f32 v[106:107], v[18:19], v[80:81]
	v_pk_mul_f32 v[108:109], v[16:17], v[78:79]
	v_pk_fma_f32 v[94:95], v[2:3], v[144:145], v[94:95]
	v_pk_fma_f32 v[96:97], v[0:1], v[142:143], v[96:97]
	v_lshlrev_b32_e32 v66, 16, v152
	v_and_b32_e32 v67, 0xffff0000, v152
	v_lshlrev_b32_e32 v68, 16, v153
	v_and_b32_e32 v69, 0xffff0000, v153
	v_lshlrev_b32_e32 v70, 16, v150
	v_and_b32_e32 v71, 0xffff0000, v150
	v_lshlrev_b32_e32 v74, 16, v151
	v_and_b32_e32 v75, 0xffff0000, v151
	v_pk_mul_f32 v[148:149], v[30:31], v[84:85]
	v_pk_mul_f32 v[150:151], v[28:29], v[82:83]
	v_pk_fma_f32 v[106:107], v[14:15], v[136:137], v[106:107]
	v_pk_fma_f32 v[108:109], v[12:13], v[134:135], v[108:109]
	v_pk_fma_f32 v[94:95], v[10:11], v[64:65], v[94:95]
	v_pk_fma_f32 v[96:97], v[8:9], v[62:63], v[96:97]
	v_pk_fma_f32 v[142:143], v[26:27], v[126:127], v[148:149]
	v_pk_fma_f32 v[144:145], v[24:25], v[122:123], v[150:151]
	v_pk_fma_f32 v[106:107], v[22:23], v[68:69], v[106:107]
	v_pk_fma_f32 v[108:109], v[20:21], v[66:67], v[108:109]
	v_pk_add_f32 v[94:95], v[38:39], v[94:95]
	v_pk_add_f32 v[96:97], v[36:37], v[96:97]
	v_pk_fma_f32 v[142:143], v[34:35], v[74:75], v[142:143]
	v_pk_fma_f32 v[144:145], v[32:33], v[70:71], v[144:145]
	v_pk_add_f32 v[94:95], v[106:107], v[94:95]
	v_pk_add_f32 v[96:97], v[108:109], v[96:97]
	v_pk_add_f32 v[94:95], v[142:143], v[94:95]
	v_pk_add_f32 v[96:97], v[144:145], v[96:97]
	v_mov_b64_e32 v[128:129], s[28:29]
	v_pk_mul_f32 v[106:107], v[94:95], v[94:95]
	v_pk_mul_f32 v[108:109], v[96:97], v[96:97]
	v_pk_fma_f32 v[106:107], v[106:107], s[26:27], v[128:129] op_sel_hi:[1,0,0] neg_lo:[1,0,0] neg_hi:[1,0,0]
	v_pk_fma_f32 v[108:109], v[108:109], s[26:27], v[128:129] op_sel_hi:[1,0,0] neg_lo:[1,0,0] neg_hi:[1,0,0]
	v_pk_mul_f32 v[106:107], v[94:95], v[106:107]
	v_pk_mul_f32 v[108:109], v[96:97], v[108:109]
	v_exp_f32_e32 v106, v106
	v_exp_f32_e32 v108, v108
	v_exp_f32_e32 v109, v109
	v_exp_f32_e32 v107, v107
	v_add_co_u32_e32 v116, vcc, s63, v116
	v_pk_add_f32 v[108:109], v[108:109], 1.0 op_sel_hi:[1,0]
	v_pk_add_f32 v[106:107], v[106:107], 1.0 op_sel_hi:[1,0]
	v_rcp_f32_e32 v108, v108
	v_rcp_f32_e32 v109, v109
	v_rcp_f32_e32 v106, v106
	v_rcp_f32_e32 v107, v107
	v_addc_co_u32_e32 v117, vcc, 0, v117, vcc
	v_pk_mul_f32 v[96:97], v[96:97], v[108:109]
	v_pk_mul_f32 v[94:95], v[94:95], v[106:107]
	v_pk_mul_f32 v[108:109], v[18:19], v[84:85]
	v_pk_mul_f32 v[142:143], v[16:17], v[82:83]
	v_pk_mul_f32 v[144:145], v[30:31], v[92:93]
	v_pk_fma_f32 v[108:109], v[14:15], v[126:127], v[108:109]
	v_add_co_u32_e32 v110, vcc, s63, v110
	v_pk_fma_f32 v[108:109], v[22:23], v[74:75], v[108:109]
	s_nop 0
	v_addc_co_u32_e32 v111, vcc, 0, v111, vcc
	v_add_co_u32_e32 v100, vcc, s63, v100
	s_waitcnt vmcnt(0) lgkmcnt(0)
	v_mov_b64_e32 v[148:149], v[158:159]
	v_addc_co_u32_e32 v101, vcc, 0, v101, vcc
	v_mov_b64_e32 v[152:153], v[154:155]
	v_mov_b64_e32 v[150:151], v[156:157]
	v_lshlrev_b32_e32 v43, 16, v88
	v_and_b32_e32 v88, 0xffff0000, v88
	v_lshlrev_b32_e32 v106, 16, v89
	v_and_b32_e32 v89, 0xffff0000, v89
	v_mul_f32_e32 v88, v97, v88
	v_mul_f32_e32 v89, v95, v89
	v_mul_f32_e32 v43, v96, v43
	v_mul_f32_e32 v94, v94, v106
	v_cvt_pk_bf16_f32 v88, v43, v88
	v_cvt_pk_bf16_f32 v89, v94, v89
	flat_store_dwordx2 v[86:87], v[88:89] offset:2560
	s_nop 1
	v_mov_b64_e32 v[94:95], v[184:185]
	v_pk_mul_f32 v[96:97], v[6:7], v[80:81]
	v_pk_mul_f32 v[106:107], v[4:5], v[78:79]
	v_pk_fma_f32 v[96:97], v[2:3], v[136:137], v[96:97]
	v_pk_fma_f32 v[106:107], v[0:1], v[134:135], v[106:107]
	v_lshlrev_b32_e32 v86, 16, v146
	v_and_b32_e32 v87, 0xffff0000, v146
	v_lshlrev_b32_e32 v88, 16, v147
	v_and_b32_e32 v89, 0xffff0000, v147
	v_pk_mul_f32 v[146:147], v[28:29], v[90:91]
	v_pk_fma_f32 v[134:135], v[12:13], v[122:123], v[142:143]
	v_pk_fma_f32 v[96:97], v[10:11], v[68:69], v[96:97]
	v_pk_fma_f32 v[106:107], v[8:9], v[66:67], v[106:107]
	v_pk_fma_f32 v[136:137], v[26:27], v[120:121], v[144:145]
	v_pk_fma_f32 v[142:143], v[24:25], v[118:119], v[146:147]
	v_pk_fma_f32 v[134:135], v[20:21], v[70:71], v[134:135]
	v_pk_add_f32 v[96:97], v[38:39], v[96:97]
	v_pk_add_f32 v[106:107], v[36:37], v[106:107]
	v_pk_fma_f32 v[136:137], v[34:35], v[88:89], v[136:137]
	v_pk_fma_f32 v[142:143], v[32:33], v[86:87], v[142:143]
	v_pk_add_f32 v[96:97], v[108:109], v[96:97]
	v_pk_add_f32 v[106:107], v[134:135], v[106:107]
	v_pk_add_f32 v[96:97], v[136:137], v[96:97]
	v_pk_add_f32 v[106:107], v[142:143], v[106:107]
	v_pk_mul_f32 v[108:109], v[96:97], v[96:97]
	v_pk_mul_f32 v[134:135], v[106:107], v[106:107]
	v_pk_fma_f32 v[108:109], v[108:109], s[26:27], v[128:129] op_sel_hi:[1,0,0] neg_lo:[1,0,0] neg_hi:[1,0,0]
	v_pk_fma_f32 v[134:135], v[134:135], s[26:27], v[128:129] op_sel_hi:[1,0,0] neg_lo:[1,0,0] neg_hi:[1,0,0]
	v_pk_mul_f32 v[108:109], v[96:97], v[108:109]
	v_pk_mul_f32 v[134:135], v[106:107], v[134:135]
	v_exp_f32_e32 v108, v108
	v_exp_f32_e32 v134, v134
	v_exp_f32_e32 v135, v135
	v_exp_f32_e32 v109, v109
	v_pk_mul_f32 v[136:137], v[30:31], v[102:103]
	v_pk_mul_f32 v[142:143], v[28:29], v[98:99]
	v_pk_add_f32 v[134:135], v[134:135], 1.0 op_sel_hi:[1,0]
	v_pk_add_f32 v[108:109], v[108:109], 1.0 op_sel_hi:[1,0]
	v_rcp_f32_e32 v134, v134
	v_rcp_f32_e32 v135, v135
	v_rcp_f32_e32 v108, v108
	v_rcp_f32_e32 v109, v109
	v_mov_b64_e32 v[146:147], v[160:161]
	v_pk_mul_f32 v[106:107], v[106:107], v[134:135]
	v_pk_mul_f32 v[134:135], v[16:17], v[90:91]
	v_pk_mul_f32 v[96:97], v[96:97], v[108:109]
	s_nop 0
	v_lshlrev_b32_e32 v43, 16, v94
	v_and_b32_e32 v94, 0xffff0000, v94
	v_lshlrev_b32_e32 v108, 16, v95
	v_and_b32_e32 v95, 0xffff0000, v95
	v_mul_f32_e32 v94, v107, v94
	v_mul_f32_e32 v95, v97, v95
	v_mul_f32_e32 v43, v106, v43
	v_mul_f32_e32 v96, v96, v108
	v_cvt_pk_bf16_f32 v94, v43, v94
	v_cvt_pk_bf16_f32 v95, v96, v95
	flat_store_dwordx2 v[116:117], v[94:95] offset:2560
	s_nop 1
	v_mov_b64_e32 v[106:107], v[186:187]
	v_pk_mul_f32 v[108:109], v[6:7], v[84:85]
	v_pk_mul_f32 v[116:117], v[4:5], v[82:83]
	v_lshlrev_b32_e32 v94, 16, v124
	v_and_b32_e32 v95, 0xffff0000, v124
	v_lshlrev_b32_e32 v96, 16, v125
	v_and_b32_e32 v97, 0xffff0000, v125
	v_pk_mul_f32 v[124:125], v[18:19], v[92:93]
	v_pk_fma_f32 v[108:109], v[2:3], v[126:127], v[108:109]
	v_pk_fma_f32 v[116:117], v[0:1], v[122:123], v[116:117]
	v_pk_fma_f32 v[122:123], v[14:15], v[120:121], v[124:125]
	v_pk_fma_f32 v[124:125], v[12:13], v[118:119], v[134:135]
	v_pk_fma_f32 v[108:109], v[10:11], v[74:75], v[108:109]
	v_pk_fma_f32 v[116:117], v[8:9], v[70:71], v[116:117]
	v_pk_fma_f32 v[126:127], v[26:27], v[132:133], v[136:137]
	v_pk_fma_f32 v[134:135], v[24:25], v[130:131], v[142:143]
	v_pk_fma_f32 v[122:123], v[22:23], v[88:89], v[122:123]
	v_pk_fma_f32 v[124:125], v[20:21], v[86:87], v[124:125]
	v_pk_add_f32 v[108:109], v[38:39], v[108:109]
	v_pk_add_f32 v[116:117], v[36:37], v[116:117]
	v_pk_fma_f32 v[126:127], v[34:35], v[96:97], v[126:127]
	v_pk_fma_f32 v[134:135], v[32:33], v[94:95], v[134:135]
	v_pk_add_f32 v[108:109], v[122:123], v[108:109]
	v_pk_add_f32 v[116:117], v[124:125], v[116:117]
	v_pk_add_f32 v[108:109], v[126:127], v[108:109]
	v_pk_add_f32 v[116:117], v[134:135], v[116:117]
	v_pk_mul_f32 v[122:123], v[108:109], v[108:109]
	v_pk_mul_f32 v[124:125], v[116:117], v[116:117]
	v_pk_fma_f32 v[122:123], v[122:123], s[26:27], v[128:129] op_sel_hi:[1,0,0] neg_lo:[1,0,0] neg_hi:[1,0,0]
	v_pk_fma_f32 v[124:125], v[124:125], s[26:27], v[128:129] op_sel_hi:[1,0,0] neg_lo:[1,0,0] neg_hi:[1,0,0]
	v_pk_mul_f32 v[122:123], v[108:109], v[122:123]
	v_pk_mul_f32 v[124:125], v[116:117], v[124:125]
	v_exp_f32_e32 v122, v122
	v_exp_f32_e32 v124, v124
	v_exp_f32_e32 v125, v125
	v_exp_f32_e32 v123, v123
	v_pk_mul_f32 v[126:127], v[30:31], v[114:115]
	v_pk_mul_f32 v[134:135], v[28:29], v[112:113]
	v_pk_add_f32 v[124:125], v[124:125], 1.0 op_sel_hi:[1,0]
	v_pk_add_f32 v[122:123], v[122:123], 1.0 op_sel_hi:[1,0]
	v_rcp_f32_e32 v124, v124
	v_rcp_f32_e32 v125, v125
	v_rcp_f32_e32 v122, v122
	v_rcp_f32_e32 v123, v123
	v_pk_mul_f32 v[116:117], v[116:117], v[124:125]
	v_pk_mul_f32 v[124:125], v[16:17], v[98:99]
	v_pk_mul_f32 v[108:109], v[108:109], v[122:123]
	s_nop 0
	v_lshlrev_b32_e32 v43, 16, v106
	v_and_b32_e32 v106, 0xffff0000, v106
	v_lshlrev_b32_e32 v122, 16, v107
	v_and_b32_e32 v107, 0xffff0000, v107
	v_mul_f32_e32 v106, v117, v106
	v_mul_f32_e32 v107, v109, v107
	v_mul_f32_e32 v43, v116, v43
	v_mul_f32_e32 v108, v108, v122
	v_cvt_pk_bf16_f32 v106, v43, v106
	v_cvt_pk_bf16_f32 v107, v108, v107
	flat_store_dwordx2 v[110:111], v[106:107] offset:2560
	s_nop 1
	v_mov_b64_e32 v[110:111], v[188:189]
	v_lshlrev_b32_e32 v106, 16, v104
	v_and_b32_e32 v107, 0xffff0000, v104
	v_lshlrev_b32_e32 v108, 16, v105
	v_and_b32_e32 v109, 0xffff0000, v105
	v_pk_mul_f32 v[104:105], v[6:7], v[92:93]
	v_pk_mul_f32 v[116:117], v[4:5], v[90:91]
	v_pk_mul_f32 v[122:123], v[18:19], v[102:103]
	v_pk_fma_f32 v[104:105], v[2:3], v[120:121], v[104:105]
	v_pk_fma_f32 v[116:117], v[0:1], v[118:119], v[116:117]
	v_pk_fma_f32 v[118:119], v[14:15], v[132:133], v[122:123]
	v_pk_fma_f32 v[104:105], v[10:11], v[88:89], v[104:105]
	v_pk_fma_f32 v[120:121], v[12:13], v[130:131], v[124:125]
	v_pk_fma_f32 v[122:123], v[26:27], v[140:141], v[126:127]
	v_pk_fma_f32 v[116:117], v[8:9], v[86:87], v[116:117]
	v_pk_fma_f32 v[118:119], v[22:23], v[96:97], v[118:119]
	v_pk_add_f32 v[104:105], v[38:39], v[104:105]
	v_pk_fma_f32 v[124:125], v[24:25], v[138:139], v[134:135]
	v_pk_fma_f32 v[120:121], v[20:21], v[94:95], v[120:121]
	v_pk_fma_f32 v[122:123], v[34:35], v[108:109], v[122:123]
	v_pk_add_f32 v[116:117], v[36:37], v[116:117]
	v_pk_add_f32 v[104:105], v[118:119], v[104:105]
	v_pk_fma_f32 v[124:125], v[32:33], v[106:107], v[124:125]
	v_pk_add_f32 v[116:117], v[120:121], v[116:117]
	v_pk_add_f32 v[104:105], v[122:123], v[104:105]
	v_pk_add_f32 v[116:117], v[124:125], v[116:117]
	v_pk_mul_f32 v[118:119], v[104:105], v[104:105]
	v_pk_mul_f32 v[120:121], v[116:117], v[116:117]
	v_pk_fma_f32 v[118:119], v[118:119], s[26:27], v[128:129] op_sel_hi:[1,0,0] neg_lo:[1,0,0] neg_hi:[1,0,0]
	v_pk_fma_f32 v[120:121], v[120:121], s[26:27], v[128:129] op_sel_hi:[1,0,0] neg_lo:[1,0,0] neg_hi:[1,0,0]
	v_pk_mul_f32 v[118:119], v[104:105], v[118:119]
	v_pk_mul_f32 v[120:121], v[116:117], v[120:121]
	v_exp_f32_e32 v118, v118
	v_exp_f32_e32 v119, v119
	v_exp_f32_e32 v120, v120
	v_exp_f32_e32 v121, v121
	v_mov_b64_e32 v[124:125], v[162:163]
	v_pk_add_f32 v[118:119], v[118:119], 1.0 op_sel_hi:[1,0]
	v_pk_add_f32 v[120:121], v[120:121], 1.0 op_sel_hi:[1,0]
	v_rcp_f32_e32 v118, v118
	v_rcp_f32_e32 v119, v119
	v_rcp_f32_e32 v120, v120
	v_rcp_f32_e32 v121, v121
	v_pk_mul_f32 v[104:105], v[104:105], v[118:119]
	v_pk_mul_f32 v[116:117], v[116:117], v[120:121]
	s_nop 0
	v_lshlrev_b32_e32 v118, 16, v111
	v_and_b32_e32 v111, 0xffff0000, v111
	v_lshlrev_b32_e32 v43, 16, v110
	v_and_b32_e32 v110, 0xffff0000, v110
	v_mul_f32_e32 v105, v105, v111
	v_mul_f32_e32 v43, v116, v43
	v_mul_f32_e32 v110, v117, v110
	v_mul_f32_e32 v116, v104, v118
	v_cvt_pk_bf16_f32 v104, v43, v110
	v_cvt_pk_bf16_f32 v105, v116, v105
	flat_store_dwordx2 v[100:101], v[104:105] offset:2560
	v_mov_b64_e32 v[104:105], v[164:165]

.LBB0_959:
	s_or_b64 exec, exec, s[10:11]
	v_add_co_u32_e32 v130, vcc, s61, v128
	v_lshlrev_b32_e32 v142, 16, v118
	s_nop 0
	v_addc_co_u32_e32 v131, vcc, 0, v129, vcc
	flat_load_dwordx2 v[138:139], v[130:131] offset:3584
	v_lshl_add_u64 v[178:179], v[116:117], 0, s[98:99]
	v_lshl_add_u64 v[180:181], v[110:111], 0, s[98:99]
	v_lshl_add_u64 v[182:183], v[100:101], 0, s[98:99]
	global_load_dwordx2 v[184:185], v[178:179], off offset:3584
	global_load_dwordx2 v[186:187], v[180:181], off offset:3584
	global_load_dwordx2 v[188:189], v[182:183], off offset:3584
	v_and_b32_e32 v143, 0xffff0000, v118
	v_lshlrev_b32_e32 v144, 16, v119
	v_and_b32_e32 v145, 0xffff0000, v119
	v_pk_mul_f32 v[118:119], v[6:7], v[64:65]
	v_pk_mul_f32 v[156:157], v[4:5], v[62:63]
	v_pk_mul_f32 v[158:159], v[18:19], v[68:69]
	v_pk_fma_f32 v[118:119], v[2:3], v[76:77], v[118:119]
	v_lshlrev_b32_e32 v136, 16, v123
	v_and_b32_e32 v137, 0xffff0000, v123
	v_pk_mul_f32 v[160:161], v[16:17], v[66:67]
	v_pk_mul_f32 v[162:163], v[30:31], v[74:75]
	v_pk_fma_f32 v[156:157], v[0:1], v[72:73], v[156:157]
	v_pk_fma_f32 v[158:159], v[14:15], v[80:81], v[158:159]
	v_pk_fma_f32 v[118:119], v[10:11], v[144:145], v[118:119]
	v_lshlrev_b32_e32 v134, 16, v122
	v_and_b32_e32 v135, 0xffff0000, v122
	v_lshlrev_b32_e32 v122, 16, v126
	v_and_b32_e32 v123, 0xffff0000, v126
	v_lshlrev_b32_e32 v126, 16, v127
	v_and_b32_e32 v127, 0xffff0000, v127
	v_pk_mul_f32 v[164:165], v[28:29], v[70:71]
	v_pk_fma_f32 v[160:161], v[12:13], v[78:79], v[160:161]
	v_pk_fma_f32 v[162:163], v[26:27], v[84:85], v[162:163]
	v_pk_fma_f32 v[156:157], v[8:9], v[142:143], v[156:157]
	v_pk_fma_f32 v[158:159], v[22:23], v[136:137], v[158:159]
	v_pk_add_f32 v[118:119], v[38:39], v[118:119]
	v_pk_fma_f32 v[164:165], v[24:25], v[82:83], v[164:165]
	v_pk_fma_f32 v[160:161], v[20:21], v[134:135], v[160:161]
	v_pk_fma_f32 v[162:163], v[34:35], v[126:127], v[162:163]
	v_pk_add_f32 v[156:157], v[36:37], v[156:157]
	v_pk_add_f32 v[118:119], v[118:119], v[158:159]
	v_pk_fma_f32 v[164:165], v[32:33], v[122:123], v[164:165]
	v_pk_add_f32 v[156:157], v[156:157], v[160:161]
	v_pk_add_f32 v[118:119], v[118:119], v[162:163]
	v_mov_b64_e32 v[154:155], s[28:29]
	v_pk_add_f32 v[156:157], v[156:157], v[164:165]
	v_pk_mul_f32 v[158:159], v[118:119], v[118:119]
	v_pk_mul_f32 v[160:161], v[156:157], v[156:157]
	v_pk_fma_f32 v[158:159], v[158:159], s[26:27], v[154:155] op_sel_hi:[1,0,0] neg_lo:[1,0,0] neg_hi:[1,0,0]
	v_pk_fma_f32 v[160:161], v[160:161], s[26:27], v[154:155] op_sel_hi:[1,0,0] neg_lo:[1,0,0] neg_hi:[1,0,0]
	v_pk_mul_f32 v[158:159], v[118:119], v[158:159]
	v_pk_mul_f32 v[160:161], v[156:157], v[160:161]
	v_exp_f32_e32 v158, v158
	v_exp_f32_e32 v159, v159
	v_exp_f32_e32 v160, v160
	v_exp_f32_e32 v161, v161
	v_add_co_u32_e32 v162, vcc, s61, v116
	v_pk_add_f32 v[158:159], v[158:159], 1.0 op_sel_hi:[1,0]
	v_pk_add_f32 v[160:161], v[160:161], 1.0 op_sel_hi:[1,0]
	v_rcp_f32_e32 v158, v158
	v_rcp_f32_e32 v159, v159
	v_rcp_f32_e32 v160, v160
	v_rcp_f32_e32 v161, v161
	v_addc_co_u32_e32 v163, vcc, 0, v117, vcc
	v_pk_mul_f32 v[118:119], v[118:119], v[158:159]
	v_pk_mul_f32 v[156:157], v[156:157], v[160:161]
	v_pk_mul_f32 v[160:161], v[16:17], v[70:71]
	v_pk_mul_f32 v[164:165], v[30:31], v[88:89]
	v_pk_mul_f32 v[170:171], v[28:29], v[86:87]
	v_pk_fma_f32 v[160:161], v[12:13], v[82:83], v[160:161]
	v_pk_fma_f32 v[170:171], v[24:25], v[90:91], v[170:171]
	v_pk_fma_f32 v[164:165], v[26:27], v[92:93], v[164:165]
	v_pk_fma_f32 v[160:161], v[20:21], v[122:123], v[160:161]
	v_pk_mul_f32 v[172:173], v[28:29], v[94:95]
	v_pk_mul_f32 v[174:175], v[28:29], v[106:107]
	v_pk_fma_f32 v[172:173], v[24:25], v[98:99], v[172:173]
	v_pk_fma_f32 v[174:175], v[24:25], v[112:113], v[174:175]
	s_waitcnt vmcnt(0) lgkmcnt(0)
	v_lshlrev_b32_e32 v158, 16, v139
	v_and_b32_e32 v139, 0xffff0000, v139
	v_lshlrev_b32_e32 v43, 16, v138
	v_and_b32_e32 v138, 0xffff0000, v138
	v_mul_f32_e32 v119, v119, v139
	v_mul_f32_e32 v43, v156, v43
	v_mul_f32_e32 v138, v157, v138
	v_mul_f32_e32 v156, v118, v158
	v_cvt_pk_bf16_f32 v118, v43, v138
	v_cvt_pk_bf16_f32 v119, v156, v119
	flat_store_dwordx2 v[130:131], v[118:119] offset:3584
	s_nop 1
	v_mov_b64_e32 v[130:131], v[184:185]
	v_pk_mul_f32 v[138:139], v[6:7], v[68:69]
	v_pk_mul_f32 v[156:157], v[4:5], v[66:67]
	v_pk_mul_f32 v[158:159], v[18:19], v[74:75]
	v_pk_fma_f32 v[156:157], v[0:1], v[78:79], v[156:157]
	v_pk_fma_f32 v[138:139], v[2:3], v[80:81], v[138:139]
	v_pk_fma_f32 v[158:159], v[14:15], v[84:85], v[158:159]
	v_pk_fma_f32 v[138:139], v[10:11], v[136:137], v[138:139]
	v_pk_fma_f32 v[156:157], v[8:9], v[134:135], v[156:157]
	v_lshlrev_b32_e32 v118, 16, v120
	v_and_b32_e32 v119, 0xffff0000, v120
	v_lshlrev_b32_e32 v120, 16, v121
	v_and_b32_e32 v121, 0xffff0000, v121
	v_pk_fma_f32 v[158:159], v[22:23], v[126:127], v[158:159]
	v_pk_add_f32 v[156:157], v[36:37], v[156:157]
	v_pk_add_f32 v[138:139], v[38:39], v[138:139]
	v_pk_fma_f32 v[164:165], v[34:35], v[120:121], v[164:165]
	v_pk_fma_f32 v[170:171], v[32:33], v[118:119], v[170:171]
	v_pk_add_f32 v[138:139], v[138:139], v[158:159]
	v_pk_add_f32 v[156:157], v[156:157], v[160:161]
	v_pk_add_f32 v[138:139], v[138:139], v[164:165]
	v_pk_add_f32 v[156:157], v[156:157], v[170:171]
	v_pk_mul_f32 v[158:159], v[138:139], v[138:139]
	v_pk_mul_f32 v[160:161], v[156:157], v[156:157]
	v_pk_fma_f32 v[158:159], v[158:159], s[26:27], v[154:155] op_sel_hi:[1,0,0] neg_lo:[1,0,0] neg_hi:[1,0,0]
	v_pk_fma_f32 v[160:161], v[160:161], s[26:27], v[154:155] op_sel_hi:[1,0,0] neg_lo:[1,0,0] neg_hi:[1,0,0]
	v_pk_mul_f32 v[158:159], v[138:139], v[158:159]
	v_pk_mul_f32 v[160:161], v[156:157], v[160:161]
	v_exp_f32_e32 v158, v158
	v_exp_f32_e32 v160, v160
	v_exp_f32_e32 v161, v161
	v_exp_f32_e32 v159, v159
	v_add_co_u32_e32 v164, vcc, s61, v110
	v_pk_add_f32 v[160:161], v[160:161], 1.0 op_sel_hi:[1,0]
	v_pk_add_f32 v[158:159], v[158:159], 1.0 op_sel_hi:[1,0]
	v_rcp_f32_e32 v160, v160
	v_rcp_f32_e32 v161, v161
	v_rcp_f32_e32 v158, v158
	v_rcp_f32_e32 v159, v159
	v_addc_co_u32_e32 v165, vcc, 0, v111, vcc
	v_pk_mul_f32 v[156:157], v[156:157], v[160:161]
	v_pk_mul_f32 v[138:139], v[138:139], v[158:159]
	v_pk_mul_f32 v[160:161], v[18:19], v[88:89]
	v_pk_mul_f32 v[170:171], v[30:31], v[96:97]
	v_pk_fma_f32 v[160:161], v[14:15], v[92:93], v[160:161]
	v_pk_fma_f32 v[170:171], v[26:27], v[102:103], v[170:171]
	v_pk_fma_f32 v[160:161], v[22:23], v[120:121], v[160:161]
	s_nop 0
	v_lshlrev_b32_e32 v43, 16, v130
	v_and_b32_e32 v130, 0xffff0000, v130
	v_lshlrev_b32_e32 v158, 16, v131
	v_and_b32_e32 v131, 0xffff0000, v131
	v_mul_f32_e32 v130, v157, v130
	v_mul_f32_e32 v131, v139, v131
	v_mul_f32_e32 v43, v156, v43
	v_mul_f32_e32 v138, v138, v158
	v_cvt_pk_bf16_f32 v130, v43, v130
	v_cvt_pk_bf16_f32 v131, v138, v131
	flat_store_dwordx2 v[162:163], v[130:131] offset:3584
	s_nop 1
	v_mov_b64_e32 v[138:139], v[186:187]
	v_pk_mul_f32 v[156:157], v[6:7], v[74:75]
	v_pk_mul_f32 v[158:159], v[4:5], v[70:71]
	v_pk_mul_f32 v[162:163], v[16:17], v[86:87]
	v_pk_fma_f32 v[158:159], v[0:1], v[82:83], v[158:159]
	v_pk_fma_f32 v[156:157], v[2:3], v[84:85], v[156:157]
	v_pk_fma_f32 v[162:163], v[12:13], v[90:91], v[162:163]
	v_pk_fma_f32 v[156:157], v[10:11], v[126:127], v[156:157]
	v_pk_fma_f32 v[158:159], v[8:9], v[122:123], v[158:159]
	v_lshlrev_b32_e32 v130, 16, v132
	v_and_b32_e32 v131, 0xffff0000, v132
	v_lshlrev_b32_e32 v132, 16, v133
	v_and_b32_e32 v133, 0xffff0000, v133
	v_pk_fma_f32 v[162:163], v[20:21], v[118:119], v[162:163]
	v_pk_add_f32 v[158:159], v[36:37], v[158:159]
	v_pk_add_f32 v[156:157], v[38:39], v[156:157]
	v_pk_fma_f32 v[170:171], v[34:35], v[132:133], v[170:171]
	v_pk_fma_f32 v[172:173], v[32:33], v[130:131], v[172:173]
	v_pk_add_f32 v[156:157], v[156:157], v[160:161]
	v_pk_add_f32 v[158:159], v[158:159], v[162:163]
	v_pk_add_f32 v[156:157], v[156:157], v[170:171]
	v_pk_add_f32 v[158:159], v[158:159], v[172:173]
	v_pk_mul_f32 v[160:161], v[156:157], v[156:157]
	v_pk_mul_f32 v[162:163], v[158:159], v[158:159]
	v_pk_fma_f32 v[160:161], v[160:161], s[26:27], v[154:155] op_sel_hi:[1,0,0] neg_lo:[1,0,0] neg_hi:[1,0,0]
	v_pk_fma_f32 v[162:163], v[162:163], s[26:27], v[154:155] op_sel_hi:[1,0,0] neg_lo:[1,0,0] neg_hi:[1,0,0]
	v_pk_mul_f32 v[160:161], v[156:157], v[160:161]
	v_pk_mul_f32 v[162:163], v[158:159], v[162:163]
	v_exp_f32_e32 v160, v160
	v_exp_f32_e32 v162, v162
	v_exp_f32_e32 v163, v163
	v_exp_f32_e32 v161, v161
	v_add_co_u32_e32 v170, vcc, s61, v100
	v_pk_add_f32 v[162:163], v[162:163], 1.0 op_sel_hi:[1,0]
	v_pk_add_f32 v[160:161], v[160:161], 1.0 op_sel_hi:[1,0]
	v_rcp_f32_e32 v162, v162
	v_rcp_f32_e32 v163, v163
	v_rcp_f32_e32 v160, v160
	v_rcp_f32_e32 v161, v161
	v_addc_co_u32_e32 v171, vcc, 0, v101, vcc
	v_pk_mul_f32 v[158:159], v[158:159], v[162:163]
	v_pk_mul_f32 v[156:157], v[156:157], v[160:161]
	v_pk_mul_f32 v[162:163], v[18:19], v[96:97]
	v_pk_mul_f32 v[172:173], v[30:31], v[108:109]
	v_pk_fma_f32 v[162:163], v[14:15], v[102:103], v[162:163]
	v_pk_fma_f32 v[172:173], v[26:27], v[114:115], v[172:173]
	v_pk_fma_f32 v[162:163], v[22:23], v[132:133], v[162:163]
	s_nop 0
	v_lshlrev_b32_e32 v43, 16, v138
	v_and_b32_e32 v138, 0xffff0000, v138
	v_lshlrev_b32_e32 v160, 16, v139
	v_and_b32_e32 v139, 0xffff0000, v139
	v_mul_f32_e32 v138, v159, v138
	v_mul_f32_e32 v139, v157, v139
	v_mul_f32_e32 v43, v158, v43
	v_mul_f32_e32 v156, v156, v160
	v_cvt_pk_bf16_f32 v138, v43, v138
	v_cvt_pk_bf16_f32 v139, v156, v139
	flat_store_dwordx2 v[164:165], v[138:139] offset:3584
	s_nop 1
	v_mov_b64_e32 v[156:157], v[188:189]
	v_pk_mul_f32 v[158:159], v[6:7], v[88:89]
	v_pk_mul_f32 v[160:161], v[4:5], v[86:87]
	v_pk_mul_f32 v[164:165], v[16:17], v[94:95]
	v_pk_fma_f32 v[160:161], v[0:1], v[90:91], v[160:161]
	v_pk_fma_f32 v[158:159], v[2:3], v[92:93], v[158:159]
	v_pk_fma_f32 v[164:165], v[12:13], v[98:99], v[164:165]
	v_pk_fma_f32 v[158:159], v[10:11], v[120:121], v[158:159]
	v_pk_fma_f32 v[160:161], v[8:9], v[118:119], v[160:161]
	v_lshlrev_b32_e32 v138, 16, v140
	v_and_b32_e32 v139, 0xffff0000, v140
	v_lshlrev_b32_e32 v140, 16, v141
	v_and_b32_e32 v141, 0xffff0000, v141
	v_pk_fma_f32 v[164:165], v[20:21], v[130:131], v[164:165]
	v_pk_add_f32 v[160:161], v[36:37], v[160:161]
	v_pk_add_f32 v[158:159], v[38:39], v[158:159]
	v_pk_fma_f32 v[172:173], v[34:35], v[140:141], v[172:173]
	v_pk_fma_f32 v[174:175], v[32:33], v[138:139], v[174:175]
	v_pk_add_f32 v[158:159], v[158:159], v[162:163]
	v_pk_add_f32 v[160:161], v[160:161], v[164:165]
	v_pk_add_f32 v[158:159], v[158:159], v[172:173]
	v_pk_add_f32 v[160:161], v[160:161], v[174:175]
	v_pk_mul_f32 v[162:163], v[158:159], v[158:159]
	v_pk_mul_f32 v[164:165], v[160:161], v[160:161]
	v_add_u32_e32 v43, 1, v168
	v_pk_fma_f32 v[164:165], v[164:165], s[26:27], v[154:155] op_sel_hi:[1,0,0] neg_lo:[1,0,0] neg_hi:[1,0,0]
	v_pk_fma_f32 v[154:155], v[162:163], s[26:27], v[154:155] op_sel_hi:[1,0,0] neg_lo:[1,0,0] neg_hi:[1,0,0]
	v_pk_mul_f32 v[162:163], v[160:161], v[164:165]
	v_pk_mul_f32 v[154:155], v[158:159], v[154:155]
	v_exp_f32_e32 v162, v162
	v_exp_f32_e32 v154, v154
	v_exp_f32_e32 v155, v155
	v_exp_f32_e32 v163, v163
	v_cmp_lt_u32_e32 vcc, v43, v53
	v_pk_add_f32 v[154:155], v[154:155], 1.0 op_sel_hi:[1,0]
	v_pk_add_f32 v[162:163], v[162:163], 1.0 op_sel_hi:[1,0]
	v_rcp_f32_e32 v154, v154
	v_rcp_f32_e32 v155, v155
	v_rcp_f32_e32 v162, v162
	v_rcp_f32_e32 v163, v163
	v_pk_mul_f32 v[154:155], v[158:159], v[154:155]
	v_pk_mul_f32 v[160:161], v[160:161], v[162:163]
	s_nop 0
	v_lshlrev_b32_e32 v159, 16, v157
	v_and_b32_e32 v157, 0xffff0000, v157
	v_lshlrev_b32_e32 v158, 16, v156
	v_and_b32_e32 v156, 0xffff0000, v156
	v_mul_f32_e32 v155, v155, v157
	v_mul_f32_e32 v158, v160, v158
	v_mul_f32_e32 v156, v161, v156
	v_mul_f32_e32 v159, v154, v159
	v_cvt_pk_bf16_f32 v154, v158, v156
	v_cvt_pk_bf16_f32 v155, v159, v155
	flat_store_dwordx2 v[170:171], v[154:155] offset:3584
	s_and_saveexec_b64 s[36:37], vcc
	s_cbranch_execz .LBB0_969
	v_cmp_gt_u32_e64 s[10:11], 61, v168
	v_mov_b32_e32 v154, v42
	v_mov_b32_e32 v155, v42
	s_and_b64 s[4:5], s[6:7], s[10:11]
	v_mov_b64_e32 v[158:159], v[154:155]
	s_and_saveexec_b64 s[46:47], s[4:5]
	s_cbranch_execz .LBB0_962
	v_add_u32_e32 v43, s34, v52
	v_add_u32_e32 v72, 0xfffac200, v43
	v_mov_b32_e32 v73, v42
	v_lshl_add_u64 v[72:73], v[44:45], 0, v[72:73]
	flat_load_dwordx2 v[158:159], v[72:73]

.LBB0_968:
	s_or_b64 exec, exec, s[10:11]
	v_add_co_u32_e32 v90, vcc, s62, v128
	v_pk_mul_f32 v[98:99], v[2:3], v[64:65]
	s_nop 0
	v_addc_co_u32_e32 v91, vcc, 0, v129, vcc
	flat_load_dwordx2 v[92:93], v[90:91] offset:1024
	v_lshl_add_u64 v[178:179], v[116:117], 0, s[100:101]
	v_lshl_add_u64 v[180:181], v[110:111], 0, s[100:101]
	v_lshl_add_u64 v[182:183], v[100:101], 0, s[100:101]
	global_load_dwordx2 v[184:185], v[178:179], off offset:-3072
	global_load_dwordx2 v[186:187], v[180:181], off offset:-3072
	global_load_dwordx2 v[188:189], v[182:183], off offset:-3072
	v_pk_mul_f32 v[102:103], v[0:1], v[62:63]
	v_lshlrev_b32_e32 v72, 16, v148
	v_and_b32_e32 v73, 0xffff0000, v148
	v_lshlrev_b32_e32 v76, 16, v149
	v_and_b32_e32 v77, 0xffff0000, v149
	v_pk_mul_f32 v[112:113], v[14:15], v[68:69]
	v_pk_mul_f32 v[114:115], v[12:13], v[66:67]
	v_pk_fma_f32 v[98:99], v[6:7], v[144:145], v[98:99]
	v_pk_fma_f32 v[102:103], v[4:5], v[142:143], v[102:103]
	v_lshlrev_b32_e32 v78, 16, v152
	v_and_b32_e32 v79, 0xffff0000, v152
	v_lshlrev_b32_e32 v80, 16, v153
	v_and_b32_e32 v81, 0xffff0000, v153
	v_pk_mul_f32 v[148:149], v[26:27], v[74:75]
	v_pk_mul_f32 v[152:153], v[24:25], v[70:71]
	v_pk_fma_f32 v[112:113], v[18:19], v[136:137], v[112:113]
	v_pk_fma_f32 v[114:115], v[16:17], v[134:135], v[114:115]
	v_pk_fma_f32 v[98:99], v[10:11], v[76:77], v[98:99]
	v_pk_fma_f32 v[102:103], v[8:9], v[72:73], v[102:103]
	v_lshlrev_b32_e32 v82, 16, v150
	v_and_b32_e32 v83, 0xffff0000, v150
	v_lshlrev_b32_e32 v84, 16, v151
	v_and_b32_e32 v85, 0xffff0000, v151
	v_pk_fma_f32 v[148:149], v[30:31], v[126:127], v[148:149]
	v_pk_fma_f32 v[152:153], v[28:29], v[122:123], v[152:153]
	v_pk_fma_f32 v[112:113], v[22:23], v[80:81], v[112:113]
	v_pk_fma_f32 v[114:115], v[20:21], v[78:79], v[114:115]
	v_pk_add_f32 v[98:99], v[38:39], v[98:99]
	v_pk_add_f32 v[102:103], v[36:37], v[102:103]
	v_pk_fma_f32 v[148:149], v[34:35], v[84:85], v[148:149]
	v_pk_fma_f32 v[152:153], v[32:33], v[82:83], v[152:153]
	v_pk_add_f32 v[98:99], v[98:99], v[112:113]
	v_pk_add_f32 v[102:103], v[102:103], v[114:115]
	v_pk_add_f32 v[98:99], v[98:99], v[148:149]
	v_pk_add_f32 v[102:103], v[102:103], v[152:153]
	v_mov_b64_e32 v[150:151], s[28:29]
	v_pk_mul_f32 v[112:113], v[98:99], v[98:99]
	v_pk_mul_f32 v[114:115], v[102:103], v[102:103]
	v_pk_fma_f32 v[112:113], v[112:113], s[26:27], v[150:151] op_sel_hi:[1,0,0] neg_lo:[1,0,0] neg_hi:[1,0,0]
	v_pk_fma_f32 v[114:115], v[114:115], s[26:27], v[150:151] op_sel_hi:[1,0,0] neg_lo:[1,0,0] neg_hi:[1,0,0]
	v_pk_mul_f32 v[112:113], v[98:99], v[112:113]
	v_pk_mul_f32 v[114:115], v[102:103], v[114:115]
	v_exp_f32_e32 v112, v112
	v_exp_f32_e32 v114, v114
	v_exp_f32_e32 v115, v115
	v_exp_f32_e32 v113, v113
	v_add_co_u32_e32 v148, vcc, s62, v116
	v_pk_add_f32 v[114:115], v[114:115], 1.0 op_sel_hi:[1,0]
	v_pk_add_f32 v[112:113], v[112:113], 1.0 op_sel_hi:[1,0]
	v_rcp_f32_e32 v114, v114
	v_rcp_f32_e32 v115, v115
	v_rcp_f32_e32 v112, v112
	v_rcp_f32_e32 v113, v113
	v_addc_co_u32_e32 v149, vcc, 0, v117, vcc
	v_pk_mul_f32 v[102:103], v[102:103], v[114:115]
	v_pk_mul_f32 v[98:99], v[98:99], v[112:113]
	v_pk_mul_f32 v[114:115], v[14:15], v[74:75]
	v_pk_mul_f32 v[152:153], v[26:27], v[88:89]
	v_pk_mul_f32 v[170:171], v[24:25], v[86:87]
	v_pk_fma_f32 v[114:115], v[18:19], v[126:127], v[114:115]
	v_pk_fma_f32 v[152:153], v[30:31], v[120:121], v[152:153]
	v_pk_fma_f32 v[170:171], v[28:29], v[118:119], v[170:171]
	v_pk_fma_f32 v[114:115], v[22:23], v[84:85], v[114:115]
	v_pk_mul_f32 v[172:173], v[24:25], v[94:95]
	v_pk_mul_f32 v[174:175], v[26:27], v[108:109]
	v_pk_fma_f32 v[172:173], v[28:29], v[130:131], v[172:173]
	v_pk_mul_f32 v[176:177], v[24:25], v[106:107]
	s_waitcnt vmcnt(0) lgkmcnt(0)
	v_lshlrev_b32_e32 v43, 16, v92
	v_and_b32_e32 v92, 0xffff0000, v92
	v_lshlrev_b32_e32 v112, 16, v93
	v_and_b32_e32 v93, 0xffff0000, v93
	v_mul_f32_e32 v92, v103, v92
	v_mul_f32_e32 v93, v99, v93
	v_mul_f32_e32 v43, v102, v43
	v_mul_f32_e32 v98, v98, v112
	v_cvt_pk_bf16_f32 v92, v43, v92
	v_cvt_pk_bf16_f32 v93, v98, v93
	flat_store_dwordx2 v[90:91], v[92:93] offset:1024
	s_nop 1
	v_mov_b64_e32 v[98:99], v[184:185]
	v_pk_mul_f32 v[102:103], v[2:3], v[68:69]
	v_pk_mul_f32 v[112:113], v[0:1], v[66:67]
	v_lshlrev_b32_e32 v90, 16, v146
	v_and_b32_e32 v91, 0xffff0000, v146
	v_lshlrev_b32_e32 v92, 16, v147
	v_and_b32_e32 v93, 0xffff0000, v147
	v_pk_mul_f32 v[146:147], v[12:13], v[70:71]
	v_pk_fma_f32 v[102:103], v[6:7], v[136:137], v[102:103]
	v_pk_fma_f32 v[112:113], v[4:5], v[134:135], v[112:113]
	v_pk_fma_f32 v[146:147], v[16:17], v[122:123], v[146:147]
	v_pk_fma_f32 v[102:103], v[10:11], v[80:81], v[102:103]
	v_pk_fma_f32 v[112:113], v[8:9], v[78:79], v[112:113]
	v_pk_fma_f32 v[146:147], v[20:21], v[82:83], v[146:147]
	v_pk_add_f32 v[102:103], v[38:39], v[102:103]
	v_pk_add_f32 v[112:113], v[36:37], v[112:113]
	v_pk_fma_f32 v[152:153], v[34:35], v[92:93], v[152:153]
	v_pk_fma_f32 v[170:171], v[32:33], v[90:91], v[170:171]
	v_pk_add_f32 v[102:103], v[102:103], v[114:115]
	v_pk_add_f32 v[112:113], v[112:113], v[146:147]
	v_pk_add_f32 v[102:103], v[102:103], v[152:153]
	v_pk_add_f32 v[112:113], v[112:113], v[170:171]
	v_pk_mul_f32 v[114:115], v[102:103], v[102:103]
	v_pk_mul_f32 v[146:147], v[112:113], v[112:113]
	v_pk_fma_f32 v[114:115], v[114:115], s[26:27], v[150:151] op_sel_hi:[1,0,0] neg_lo:[1,0,0] neg_hi:[1,0,0]
	v_pk_fma_f32 v[146:147], v[146:147], s[26:27], v[150:151] op_sel_hi:[1,0,0] neg_lo:[1,0,0] neg_hi:[1,0,0]
	v_pk_mul_f32 v[114:115], v[102:103], v[114:115]
	v_pk_mul_f32 v[146:147], v[112:113], v[146:147]
	v_exp_f32_e32 v114, v114
	v_exp_f32_e32 v146, v146
	v_exp_f32_e32 v147, v147
	v_exp_f32_e32 v115, v115
	v_add_co_u32_e32 v152, vcc, s62, v110
	v_pk_add_f32 v[146:147], v[146:147], 1.0 op_sel_hi:[1,0]
	v_pk_add_f32 v[114:115], v[114:115], 1.0 op_sel_hi:[1,0]
	v_rcp_f32_e32 v146, v146
	v_rcp_f32_e32 v147, v147
	v_rcp_f32_e32 v114, v114
	v_rcp_f32_e32 v115, v115
	v_addc_co_u32_e32 v153, vcc, 0, v111, vcc
	v_pk_mul_f32 v[112:113], v[112:113], v[146:147]
	v_pk_mul_f32 v[102:103], v[102:103], v[114:115]
	v_pk_mul_f32 v[146:147], v[14:15], v[88:89]
	v_pk_mul_f32 v[170:171], v[26:27], v[96:97]
	v_pk_fma_f32 v[146:147], v[18:19], v[120:121], v[146:147]
	v_pk_fma_f32 v[170:171], v[30:31], v[132:133], v[170:171]
	v_pk_fma_f32 v[146:147], v[22:23], v[92:93], v[146:147]
	s_nop 0
	v_lshlrev_b32_e32 v43, 16, v98
	v_and_b32_e32 v98, 0xffff0000, v98
	v_lshlrev_b32_e32 v114, 16, v99
	v_and_b32_e32 v99, 0xffff0000, v99
	v_mul_f32_e32 v98, v113, v98
	v_mul_f32_e32 v99, v103, v99
	v_mul_f32_e32 v43, v112, v43
	v_mul_f32_e32 v102, v102, v114
	v_cvt_pk_bf16_f32 v98, v43, v98
	v_cvt_pk_bf16_f32 v99, v102, v99
	flat_store_dwordx2 v[148:149], v[98:99] offset:1024
	s_nop 1
	v_mov_b64_e32 v[112:113], v[186:187]
	v_lshlrev_b32_e32 v98, 16, v124
	v_and_b32_e32 v99, 0xffff0000, v124
	v_lshlrev_b32_e32 v102, 16, v125
	v_and_b32_e32 v103, 0xffff0000, v125
	v_pk_mul_f32 v[114:115], v[2:3], v[74:75]
	v_pk_mul_f32 v[124:125], v[0:1], v[70:71]
	v_pk_mul_f32 v[148:149], v[12:13], v[86:87]
	v_pk_fma_f32 v[114:115], v[6:7], v[126:127], v[114:115]
	v_pk_fma_f32 v[124:125], v[4:5], v[122:123], v[124:125]
	v_pk_fma_f32 v[148:149], v[16:17], v[118:119], v[148:149]
	v_pk_fma_f32 v[114:115], v[10:11], v[84:85], v[114:115]
	v_pk_fma_f32 v[124:125], v[8:9], v[82:83], v[124:125]
	v_pk_fma_f32 v[148:149], v[20:21], v[90:91], v[148:149]
	v_pk_add_f32 v[114:115], v[38:39], v[114:115]
	v_pk_add_f32 v[124:125], v[36:37], v[124:125]
	v_pk_fma_f32 v[170:171], v[34:35], v[102:103], v[170:171]
	v_pk_fma_f32 v[172:173], v[32:33], v[98:99], v[172:173]
	v_pk_add_f32 v[114:115], v[114:115], v[146:147]
	v_pk_add_f32 v[124:125], v[124:125], v[148:149]
	v_pk_add_f32 v[114:115], v[114:115], v[170:171]
	v_pk_add_f32 v[124:125], v[124:125], v[172:173]
	v_pk_mul_f32 v[146:147], v[114:115], v[114:115]
	v_pk_mul_f32 v[148:149], v[124:125], v[124:125]
	v_pk_fma_f32 v[146:147], v[146:147], s[26:27], v[150:151] op_sel_hi:[1,0,0] neg_lo:[1,0,0] neg_hi:[1,0,0]
	v_pk_fma_f32 v[148:149], v[148:149], s[26:27], v[150:151] op_sel_hi:[1,0,0] neg_lo:[1,0,0] neg_hi:[1,0,0]
	v_pk_mul_f32 v[146:147], v[114:115], v[146:147]
	v_pk_mul_f32 v[148:149], v[124:125], v[148:149]
	v_exp_f32_e32 v146, v146
	v_exp_f32_e32 v148, v148
	v_exp_f32_e32 v149, v149
	v_exp_f32_e32 v147, v147
	v_add_co_u32_e32 v170, vcc, s62, v100
	v_pk_add_f32 v[148:149], v[148:149], 1.0 op_sel_hi:[1,0]
	v_pk_add_f32 v[146:147], v[146:147], 1.0 op_sel_hi:[1,0]
	v_rcp_f32_e32 v148, v148
	v_rcp_f32_e32 v149, v149
	v_rcp_f32_e32 v146, v146
	v_rcp_f32_e32 v147, v147
	v_addc_co_u32_e32 v171, vcc, 0, v101, vcc
	v_pk_mul_f32 v[124:125], v[124:125], v[148:149]
	v_pk_mul_f32 v[114:115], v[114:115], v[146:147]
	v_mov_b64_e32 v[148:149], v[158:159]
	v_pk_fma_f32 v[158:159], v[30:31], v[140:141], v[174:175]
	v_pk_fma_f32 v[174:175], v[28:29], v[138:139], v[176:177]
	s_nop 0
	v_lshlrev_b32_e32 v43, 16, v112
	v_and_b32_e32 v112, 0xffff0000, v112
	v_lshlrev_b32_e32 v146, 16, v113
	v_and_b32_e32 v113, 0xffff0000, v113
	v_mul_f32_e32 v112, v125, v112
	v_mul_f32_e32 v113, v115, v113
	v_mul_f32_e32 v43, v124, v43
	v_mul_f32_e32 v114, v114, v146
	v_cvt_pk_bf16_f32 v112, v43, v112
	v_cvt_pk_bf16_f32 v113, v114, v113
	flat_store_dwordx2 v[152:153], v[112:113] offset:1024
	s_nop 1
	v_mov_b64_e32 v[172:173], v[188:189]
	v_lshlrev_b32_e32 v112, 16, v104
	v_and_b32_e32 v113, 0xffff0000, v104
	v_lshlrev_b32_e32 v114, 16, v105
	v_and_b32_e32 v115, 0xffff0000, v105
	v_pk_mul_f32 v[104:105], v[2:3], v[88:89]
	v_pk_mul_f32 v[124:125], v[0:1], v[86:87]
	v_pk_mul_f32 v[146:147], v[14:15], v[96:97]
	v_pk_mul_f32 v[152:153], v[12:13], v[94:95]
	v_pk_fma_f32 v[104:105], v[6:7], v[120:121], v[104:105]
	v_pk_fma_f32 v[124:125], v[4:5], v[118:119], v[124:125]
	v_pk_fma_f32 v[146:147], v[18:19], v[132:133], v[146:147]
	v_pk_fma_f32 v[152:153], v[16:17], v[130:131], v[152:153]
	v_pk_fma_f32 v[104:105], v[10:11], v[92:93], v[104:105]
	v_pk_fma_f32 v[124:125], v[8:9], v[90:91], v[124:125]
	v_pk_fma_f32 v[146:147], v[22:23], v[102:103], v[146:147]
	v_pk_fma_f32 v[152:153], v[20:21], v[98:99], v[152:153]
	v_pk_add_f32 v[104:105], v[38:39], v[104:105]
	v_pk_add_f32 v[124:125], v[36:37], v[124:125]
	v_pk_fma_f32 v[158:159], v[34:35], v[114:115], v[158:159]
	v_pk_fma_f32 v[174:175], v[32:33], v[112:113], v[174:175]
	v_pk_add_f32 v[104:105], v[104:105], v[146:147]
	v_pk_add_f32 v[124:125], v[124:125], v[152:153]
	v_pk_add_f32 v[104:105], v[104:105], v[158:159]
	v_pk_add_f32 v[158:159], v[124:125], v[174:175]
	v_pk_mul_f32 v[124:125], v[104:105], v[104:105]
	v_pk_mul_f32 v[146:147], v[158:159], v[158:159]
	v_pk_fma_f32 v[124:125], v[124:125], s[26:27], v[150:151] op_sel_hi:[1,0,0] neg_lo:[1,0,0] neg_hi:[1,0,0]
	v_pk_fma_f32 v[146:147], v[146:147], s[26:27], v[150:151] op_sel_hi:[1,0,0] neg_lo:[1,0,0] neg_hi:[1,0,0]
	v_pk_mul_f32 v[124:125], v[104:105], v[124:125]
	v_pk_mul_f32 v[146:147], v[158:159], v[146:147]
	v_exp_f32_e32 v124, v124
	v_exp_f32_e32 v146, v146
	v_exp_f32_e32 v147, v147
	v_exp_f32_e32 v125, v125
	v_mov_b64_e32 v[152:153], v[154:155]
	v_mov_b64_e32 v[150:151], v[156:157]
	v_pk_add_f32 v[146:147], v[146:147], 1.0 op_sel_hi:[1,0]
	v_pk_add_f32 v[124:125], v[124:125], 1.0 op_sel_hi:[1,0]
	v_rcp_f32_e32 v154, v146
	v_rcp_f32_e32 v155, v147
	v_rcp_f32_e32 v156, v124
	v_rcp_f32_e32 v157, v125
	v_mov_b64_e32 v[146:147], v[160:161]
	v_pk_mul_f32 v[154:155], v[158:159], v[154:155]
	v_mov_b64_e32 v[124:125], v[162:163]
	v_pk_mul_f32 v[104:105], v[104:105], v[156:157]
	s_nop 0
	v_and_b32_e32 v158, 0xffff0000, v173
	v_lshlrev_b32_e32 v43, 16, v172
	v_and_b32_e32 v156, 0xffff0000, v172
	v_lshlrev_b32_e32 v157, 16, v173
	v_mul_f32_e32 v105, v105, v158
	v_mul_f32_e32 v43, v154, v43
	v_mul_f32_e32 v154, v155, v156
	v_mul_f32_e32 v155, v104, v157
	v_cvt_pk_bf16_f32 v104, v43, v154
	v_cvt_pk_bf16_f32 v105, v155, v105
	flat_store_dwordx2 v[170:171], v[104:105] offset:1024
	v_mov_b64_e32 v[104:105], v[164:165]
